# epiz bias wait only when bias loads were issued; ffn-down halo patch loads batched
# baseline (speedup 1.0000x reference)
; __device__ __forceinline__ unsigned cvt_pk_bf16(float lo, float hi) { unsigned r; asm("v_cvt_pk_bf16_f32 %0, %1, %2" : "=v"(r) : "v"(lo), "v"(hi)); return r; }
; __device__ __forceinline__ float siluf_(float x) { return x * sigmoidf_(x); }
; __global__ void __launch_bounds__(NTHREADS) mega_fwd(Params p) {
;     ...
;                     for (int idx = tid; idx < 2 * 704; idx += NTHREADS) { const int r = idx / 704, c = (idx - r * 704) * 4;
;                         f32x4 gsum = *(const f32x4*)(cb + c), vsum = *(const f32x4*)(cb + FFW + c);
; #pragma unroll
;                         for (int k = 0; k < 3; ++k) { const int j = r - 2 + k; const float* zr = (j < 0) ? ZS + ((size_t)(uu.pm - 1) * 4 + 4 + j) * 5632 : ZS + ((size_t)uu.pm * 4 + j) * 5632;
;                             gsum += *(const f32x4*)(cw + k * 5632 + c) * *(const f32x4*)(zr + c); vsum += *(const f32x4*)(cw + k * 5632 + FFW + c) * *(const f32x4*)(zr + FFW + c); }
;                         u32x2 w; w.x = cvt_pk_bf16(siluf_(gsum[0]) * vsum[0], siluf_(gsum[1]) * vsum[1]); w.y = cvt_pk_bf16(siluf_(gsum[2]) * vsum[2], siluf_(gsum[3]) * vsum[3]);
;                         *(u32x2*)(A2 + (size_t)(uu.pm * 256 + r) * FFW + c) = w; } }
.LBB0_263:
	s_or_b64 exec, exec, s[0:1]
	v_mov_b64_e32 v[52:53], s[4:5]
	v_mad_u64_u32 v[54:55], s[0:1], v48, s76, v[52:53]
	v_mov_b32_e32 v0, v55
	v_mad_u64_u32 v[52:53], s[0:1], v49, s76, v[0:1]
	v_mov_b32_e32 v55, v52
	v_lshl_add_u64 v[56:57], s[28:29], 0, v[46:47]
	v_lshl_add_u64 v[54:55], v[54:55], 0, v[46:47]
	global_load_dwordx4 v[60:63], v[56:57], off
	v_add_co_u32_e32 v52, vcc, s63, v54
	v_lshl_add_u64 v[56:57], s[30:31], 0, v[46:47]
	global_load_dwordx4 v[64:67], v[54:55], off
	v_addc_co_u32_e32 v53, vcc, 0, v55, vcc
	global_load_dwordx4 v[68:71], v[56:57], off
	global_load_dwordx4 v[72:75], v[52:53], off offset:3072
	s_waitcnt vmcnt(0) lgkmcnt(0)
	v_pk_fma_f32 v[2:3], v[18:19], v[22:23], v[2:3]
	v_pk_fma_f32 v[8:9], v[12:13], v[16:17], v[8:9]
	v_pk_fma_f32 v[6:7], v[10:11], v[14:15], v[6:7]
	v_pk_fma_f32 v[16:17], v[34:35], v[38:39], v[2:3]
	v_pk_fma_f32 v[12:13], v[26:27], v[30:31], v[6:7]
	v_pk_fma_f32 v[4:5], v[20:21], v[24:25], v[4:5]
	v_pk_fma_f32 v[10:11], v[28:29], v[32:33], v[8:9]
	v_pk_fma_f32 v[14:15], v[36:37], v[40:41], v[4:5]
	v_pk_fma_f32 v[12:13], v[60:61], v[64:65], v[12:13]
	v_pk_fma_f32 v[10:11], v[62:63], v[66:67], v[10:11]
	v_mul_f32_e32 v0, 0xbfb8aa3b, v12
	v_exp_f32_e32 v0, v0
	v_pk_fma_f32 v[2:3], v[68:69], v[72:73], v[16:17]
	v_add_f32_e32 v0, 1.0, v0
	v_div_scale_f32 v6, s[0:1], v0, v0, 1.0
	v_rcp_f32_e32 v7, v6
	v_pk_fma_f32 v[4:5], v[70:71], v[74:75], v[14:15]
	v_fma_f32 v8, -v6, v7, 1.0
	v_fmac_f32_e32 v7, v8, v7
	v_div_scale_f32 v8, vcc, 1.0, v0, 1.0
	v_mul_f32_e32 v9, v8, v7
	v_fma_f32 v14, -v6, v9, v8
	v_fmac_f32_e32 v9, v14, v7
	v_fma_f32 v6, -v6, v9, v8
	v_div_fmas_f32 v6, v6, v7, v9
	v_div_fixup_f32 v0, v6, v0, 1.0
	v_mul_f32_e32 v0, v12, v0
	v_mul_f32_e32 v0, v2, v0
	v_mul_f32_e32 v2, 0xbfb8aa3b, v13
	v_exp_f32_e32 v2, v2
	s_nop 0
	v_add_f32_e32 v2, 1.0, v2
	v_div_scale_f32 v6, s[0:1], v2, v2, 1.0
	v_rcp_f32_e32 v7, v6
	s_nop 0
	v_fma_f32 v8, -v6, v7, 1.0
	v_fmac_f32_e32 v7, v8, v7
	v_div_scale_f32 v8, vcc, 1.0, v2, 1.0
	v_mul_f32_e32 v9, v8, v7
	v_fma_f32 v12, -v6, v9, v8
	v_fmac_f32_e32 v9, v12, v7
	v_fma_f32 v6, -v6, v9, v8
	v_div_fmas_f32 v6, v6, v7, v9
	v_div_fixup_f32 v2, v6, v2, 1.0
	v_mul_f32_e32 v2, v13, v2
	v_mul_f32_e32 v2, v3, v2
	v_cvt_pk_bf16_f32 v2, v0, v2
	v_mul_f32_e32 v0, 0xbfb8aa3b, v10
	v_exp_f32_e32 v0, v0
	s_nop 0
	v_add_f32_e32 v0, 1.0, v0
	v_div_scale_f32 v3, s[0:1], v0, v0, 1.0
	v_rcp_f32_e32 v6, v3
	s_nop 0
	v_fma_f32 v7, -v3, v6, 1.0
	v_fmac_f32_e32 v6, v7, v6
	v_div_scale_f32 v7, vcc, 1.0, v0, 1.0
	v_mul_f32_e32 v8, v7, v6
	v_fma_f32 v9, -v3, v8, v7
	v_fmac_f32_e32 v8, v9, v6
	v_fma_f32 v3, -v3, v8, v7
	v_div_fmas_f32 v3, v3, v6, v8
	v_div_fixup_f32 v0, v3, v0, 1.0
	v_mul_f32_e32 v3, 0xbfb8aa3b, v11
	v_exp_f32_e32 v3, v3
	v_mul_f32_e32 v0, v10, v0
	v_mul_f32_e32 v0, v4, v0
	v_add_f32_e32 v3, 1.0, v3
	v_div_scale_f32 v4, s[0:1], v3, v3, 1.0
	v_rcp_f32_e32 v6, v4
	s_nop 0
	v_fma_f32 v7, -v4, v6, 1.0
	v_fmac_f32_e32 v6, v7, v6
	v_div_scale_f32 v7, vcc, 1.0, v3, 1.0
	v_mul_f32_e32 v8, v7, v6
	v_fma_f32 v9, -v4, v8, v7
	v_fmac_f32_e32 v8, v9, v6
	v_fma_f32 v4, -v4, v8, v7
	v_div_fmas_f32 v4, v4, v6, v8
	v_div_fixup_f32 v3, v4, v3, 1.0
	v_mul_f32_e32 v3, v11, v3
	v_mul_f32_e32 v3, v5, v3
	v_cvt_pk_bf16_f32 v3, v0, v3
	v_add_u32_e32 v0, s9, v44
	v_mov_b64_e32 v[4:5], s[70:71]
	v_mad_i64_i32 v[4:5], s[0:1], v0, s77, v[4:5]
	s_movk_i32 s0, 0x37f
	v_add_u32_e32 v0, 0x200, v50
	v_cmp_lt_i32_e32 vcc, s0, v50
	v_lshl_add_u64 v[4:5], v[42:43], 1, v[4:5]
	s_or_b64 s[40:41], vcc, s[40:41]
	v_mov_b32_e32 v50, v0
	global_store_dwordx2 v[4:5], v[2:3], off
	s_andn2_b64 exec, exec, s[40:41]
	s_cbranch_execz .LBB0_252

;     __device__ __forceinline__ void operator()(const f32x4 (&acc)[2][2][4][2], const Unit& u, int wr, int wc, int fr, int fq) const {
;     ...
;         f32x4 bv[2][2];
; #pragma unroll
;         for (int bj = 0; bj < 2; ++bj)
; #pragma unroll
;             for (int n = 0; n < 2; ++n) bv[bj][n] = bias ? *(const f32x4*)(bias + bcol0 + bj * HALF + 4 * n) : (f32x4){0.f, 0.f, 0.f, 0.f};
.LBB0_445:
	s_and_b64 vcc, exec, s[8:9]
	v_mov_b32_e32 v67, 0
	v_mov_b32_e32 v68, 0
	v_mov_b32_e32 v69, 0
	s_cbranch_vccnz .LBB0_447
	global_load_dwordx4 v[66:69], v[156:157], off offset:528
	s_waitcnt vmcnt(0)

; __device__ __forceinline__ f32x2v gelu_tanh_pk(f32x2v x) {
;     const f32x2v x2 = x * x, u = x * (x2 * 0.044715f + 1.0f), e = u * (-2.3022082f);
;     f32x2v t; t.x = __builtin_amdgcn_exp2f(e.x); t.y = __builtin_amdgcn_exp2f(e.y);
;     const f32x2v d = t + 1.0f; f32x2v r; r.x = __builtin_amdgcn_rcpf(d.x); r.y = __builtin_amdgcn_rcpf(d.y);
;     return x * r; }
;     __device__ __forceinline__ void operator()(const f32x4 (&acc)[2][2][4][2], const Unit& u, int wr, int wc, int fr, int fq) const {
;     ...
;                 for (int bj = 0; bj < 2; ++bj) { f32x4 v0 = acc[ai][bj][m][0] * rs + bv[bj][0], v1 = acc[ai][bj][m][1] * rs + bv[bj][1];
;                     if (act) { const f32x2v a = gelu_tanh_pk((f32x2v){v0[0], v0[1]}), b = gelu_tanh_pk((f32x2v){v0[2], v0[3]}), c = gelu_tanh_pk((f32x2v){v1[0], v1[1]}), d = gelu_tanh_pk((f32x2v){v1[2], v1[3]});
;                         v0 = (f32x4){a.x, a.y, b.x, b.y}; v1 = (f32x4){c.x, c.y, d.x, d.y}; }
.LBB0_450:
	s_cmp_lt_i32 s89, s17
	s_cselect_b64 s[8:9], -1, 0
	s_cmp_ge_i32 s89, s17
	s_waitcnt lgkmcnt(0)
	v_pk_fma_f32 v[144:145], v[144:145], v[160:161], v[80:81] op_sel_hi:[1,0,1]
	v_pk_fma_f32 v[156:157], v[142:143], v[160:161], v[78:79] op_sel_hi:[1,0,1]
	v_pk_fma_f32 v[142:143], v[140:141], v[160:161], v[76:77] op_sel_hi:[1,0,1]
	v_pk_fma_f32 v[158:159], v[138:139], v[160:161], v[74:75] op_sel_hi:[1,0,1]
	s_cbranch_scc1 .LBB0_452
	v_pk_mul_f32 v[138:139], v[144:145], v[144:145]
	v_pk_mul_f32 v[140:141], v[156:157], v[156:157]
	v_pk_mul_f32 v[166:167], v[142:143], v[142:143]
	v_pk_mul_f32 v[168:169], v[158:159], v[158:159]
	v_pk_fma_f32 v[140:141], v[140:141], s[86:87], 1.0 op_sel_hi:[1,0,0]
	v_pk_fma_f32 v[138:139], v[138:139], s[86:87], 1.0 op_sel_hi:[1,0,0]
	v_pk_fma_f32 v[168:169], v[168:169], s[86:87], 1.0 op_sel_hi:[1,0,0]
	v_pk_fma_f32 v[166:167], v[166:167], s[86:87], 1.0 op_sel_hi:[1,0,0]
	v_pk_mul_f32 v[140:141], v[156:157], v[140:141]
	v_pk_mul_f32 v[138:139], v[144:145], v[138:139]
	v_pk_mul_f32 v[168:169], v[158:159], v[168:169]
	v_pk_mul_f32 v[166:167], v[142:143], v[166:167]
	v_pk_mul_f32 v[140:141], v[140:141], s[94:95] op_sel_hi:[1,0]
	v_pk_mul_f32 v[138:139], v[138:139], s[94:95] op_sel_hi:[1,0]
	v_pk_mul_f32 v[168:169], v[168:169], s[94:95] op_sel_hi:[1,0]
	v_pk_mul_f32 v[166:167], v[166:167], s[94:95] op_sel_hi:[1,0]
	v_exp_f32_e32 v140, v140
	v_exp_f32_e32 v141, v141
	v_exp_f32_e32 v138, v138
	v_exp_f32_e32 v139, v139
	v_exp_f32_e32 v168, v168
	v_exp_f32_e32 v169, v169
	v_exp_f32_e32 v166, v166
	v_exp_f32_e32 v167, v167
	v_pk_add_f32 v[140:141], v[140:141], 1.0 op_sel_hi:[1,0]
	v_pk_add_f32 v[138:139], v[138:139], 1.0 op_sel_hi:[1,0]
	v_pk_add_f32 v[168:169], v[168:169], 1.0 op_sel_hi:[1,0]
	v_pk_add_f32 v[166:167], v[166:167], 1.0 op_sel_hi:[1,0]
	v_rcp_f32_e32 v140, v140
	v_rcp_f32_e32 v141, v141
	v_rcp_f32_e32 v138, v138
	v_rcp_f32_e32 v139, v139
	v_rcp_f32_e32 v168, v168
	v_rcp_f32_e32 v169, v169
	v_rcp_f32_e32 v166, v166
	v_rcp_f32_e32 v167, v167
	v_pk_mul_f32 v[156:157], v[156:157], v[140:141]
	v_pk_mul_f32 v[144:145], v[144:145], v[138:139]
	v_pk_mul_f32 v[158:159], v[158:159], v[168:169]
	v_pk_mul_f32 v[142:143], v[142:143], v[166:167]
